# MLA: waves 0-3 meet the barrier behind their 3rd PV MFMA (4th behind the barrier)
# baseline (speedup 1.0000x reference)
; __device__ __forceinline__ void finishSM9(f32x16& p0, f32x16& p1, float alpha, float& l_reg, v8i32& p8) {
; #pragma unroll
;   for (int r = 0; r < 16; ++r) { p0[r] = __builtin_amdgcn_exp2f(p0[r]); p1[r] = __builtin_amdgcn_exp2f(p1[r]); }
;   float ps = 0;
; #pragma unroll
;   for (int r = 0; r < 16; ++r) ps += p0[r];
; #pragma unroll
;   for (int r = 0; r < 16; ++r) ps += p1[r];
;   { auto rr = __builtin_amdgcn_permlane32_swap(__float_as_uint(ps), __float_as_uint(ps), false, false);
;     ps = __uint_as_float(rr[0]) + __uint_as_float(rr[1]); }
;   l_reg = l_reg * alpha + ps;
; #pragma unroll
;   for (int g = 0; g < 4; ++g) {
;     int w = __builtin_amdgcn_cvt_pk_fp8_f32(p0[4 * g], p0[4 * g + 1], 0, false); p8[g] = __builtin_amdgcn_cvt_pk_fp8_f32(p0[4 * g + 2], p0[4 * g + 3], w, true);
;     int u = __builtin_amdgcn_cvt_pk_fp8_f32(p1[4 * g], p1[4 * g + 1], 0, false); p8[4 + g] = __builtin_amdgcn_cvt_pk_fp8_f32(p1[4 * g + 2], p1[4 * g + 3], u, true); }
; }
; __device__ __forceinline__ void pv8(f32x16* o, const char* Vt, const v8i32 p8, int r32, int hi) {
;   const int sw = (r32 >> 2) & 3, a0 = r32 * 64 + (((hi * 2) ^ sw) << 4), a1 = r32 * 64 + (((hi * 2 + 1) ^ sw) << 4);
; #pragma unroll
;   for (int d0 = 0; d0 < 4; ++d0) {
;     const v8i32 vf = cat8(*reinterpret_cast<const v4i32*>(Vt + d0 * 2048 + a0), *reinterpret_cast<const v4i32*>(Vt + d0 * 2048 + a1));
;     o[d0] = __builtin_amdgcn_mfma_scale_f32_32x32x64_f8f6f4(p8, vf, o[d0], 0, 0, 0, 127, 0, 127); }
; }
; __device__ __forceinline__ void qkt9(f32x16& p0, f32x16& p1, const char* Kn, const char* Kr, const v8i32* qf, const float init, int r32, int hi) {
; #pragma unroll
;   for (int r = 0; r < 16; ++r) { p0[r] = init; p1[r] = init; }
; #pragma unroll
;   for (int s = 0; s < 2; ++s) { const int c0 = s * 4 + hi * 2;
;     const v8i32 a0 = cat8(*reinterpret_cast<const v4i32*>(Kn + KN8SW(r32, c0)), *reinterpret_cast<const v4i32*>(Kn + KN8SW(r32, c0 + 1)));
;     const v8i32 a1 = cat8(*reinterpret_cast<const v4i32*>(Kn + 4096 + KN8SW(r32, c0)), *reinterpret_cast<const v4i32*>(Kn + 4096 + KN8SW(r32, c0 + 1)));
;     p0 = __builtin_amdgcn_mfma_scale_f32_32x32x64_f8f6f4(a0, qf[s], p0, 0, 0, 0, 127, 0, 124);
;     p1 = __builtin_amdgcn_mfma_scale_f32_32x32x64_f8f6f4(a1, qf[s], p1, 0, 0, 0, 127, 0, 124); }
;   { const int c0 = hi * 2;
.LBB0_1321:
	global_load_dwordx4 v[158:161], v176, s[18:19]
	global_load_dwordx4 v[162:165], v178, s[16:17]
	global_load_dwordx4 v[154:157], v[180:181], off
	ds_read_b128 v[114:117], v215 offset:24576
	ds_read_b128 v[118:121], v216 offset:24576
	ds_read_b128 v[222:225], v215 offset:28672
	ds_read_b128 v[226:229], v216 offset:28672
	v_add_u32_e32 v176, 0x2000, v176
	v_add_u32_e32 v178, 0x20000, v178
	s_mov_b64 s[20:21], 0x1000
	v_lshl_add_u64 v[180:181], v[180:181], 0, s[20:21]
	v_exp_f32_e32 v0, v82
	v_exp_f32_e32 v177, v83
	v_exp_f32_e32 v179, v84
	v_exp_f32_e32 v254, v85
	v_add_f32_e32 v219, v0, v177
	v_cvt_pk_fp8_f32 v246, v0, v177
	v_add_f32_e32 v219, v179, v219
	v_add_f32_e32 v219, v254, v219
	v_cvt_pk_fp8_f32 v246, v179, v254 op_sel:[0,0,1]
	s_waitcnt lgkmcnt(2)
	v_mfma_scale_f32_32x32x64_f8f6f4 v[114:129], v[114:121], v[146:153], v[230:245], v194, v193 op_sel_hi:[0,0,0]
	v_exp_f32_e32 v0, v86
	v_exp_f32_e32 v177, v87
	v_exp_f32_e32 v179, v88
	v_exp_f32_e32 v254, v89
	v_add_f32_e32 v219, v0, v219
	v_add_f32_e32 v219, v177, v219
	v_cvt_pk_fp8_f32 v247, v0, v177
	v_add_f32_e32 v219, v179, v219
	v_add_f32_e32 v219, v254, v219
	v_cvt_pk_fp8_f32 v247, v179, v254 op_sel:[0,0,1]
	ds_read_b128 v[82:85], v213 offset:24576
	ds_read_b128 v[86:89], v214 offset:24576
	s_waitcnt lgkmcnt(2)
	v_mfma_scale_f32_32x32x64_f8f6f4 v[98:113], v[222:229], v[146:153], v[230:245], v194, v193 op_sel_hi:[0,0,0]
	ds_read_b128 v[222:225], v213 offset:28672
	ds_read_b128 v[226:229], v214 offset:28672
	v_exp_f32_e32 v0, v90
	v_exp_f32_e32 v177, v91
	v_exp_f32_e32 v179, v92
	v_exp_f32_e32 v254, v93
	v_add_f32_e32 v219, v0, v219
	v_add_f32_e32 v219, v177, v219
	v_cvt_pk_fp8_f32 v248, v0, v177
	v_add_f32_e32 v219, v179, v219
	v_add_f32_e32 v219, v254, v219
	v_cvt_pk_fp8_f32 v248, v179, v254 op_sel:[0,0,1]
	v_exp_f32_e32 v0, v94
	v_exp_f32_e32 v177, v95
	v_exp_f32_e32 v179, v96
	v_exp_f32_e32 v254, v97
	v_add_f32_e32 v219, v0, v219
	v_add_f32_e32 v219, v177, v219
	v_cvt_pk_fp8_f32 v249, v0, v177
	v_add_f32_e32 v219, v179, v219
	v_add_f32_e32 v219, v254, v219
	v_cvt_pk_fp8_f32 v249, v179, v254 op_sel:[0,0,1]
	ds_read_b128 v[90:93], v185 offset:36864
	ds_read_b128 v[94:97], v186 offset:36864
	s_waitcnt lgkmcnt(4)
	v_mfma_scale_f32_32x32x64_f8f6f4 v[114:129], v[82:89], v[138:145], v[114:129], v194, v193 op_sel_hi:[0,0,0]
	v_exp_f32_e32 v0, v66
	v_exp_f32_e32 v177, v67
	v_exp_f32_e32 v179, v68
	v_exp_f32_e32 v254, v69
	v_add_f32_e32 v219, v0, v219
	v_add_f32_e32 v219, v177, v219
	v_cvt_pk_fp8_f32 v250, v0, v177
	v_add_f32_e32 v219, v179, v219
	v_add_f32_e32 v219, v254, v219
	v_cvt_pk_fp8_f32 v250, v179, v254 op_sel:[0,0,1]
	s_waitcnt lgkmcnt(2)
	v_mfma_scale_f32_32x32x64_f8f6f4 v[98:113], v[222:229], v[138:145], v[98:113], v194, v193 op_sel_hi:[0,0,0]
	ds_read_b128 v[222:225], v185 offset:38912
	ds_read_b128 v[226:229], v186 offset:38912
	v_exp_f32_e32 v0, v70
	v_exp_f32_e32 v177, v71
	v_exp_f32_e32 v179, v72
	v_exp_f32_e32 v254, v73
	v_add_f32_e32 v219, v0, v219
	v_add_f32_e32 v219, v177, v219
	v_cvt_pk_fp8_f32 v251, v0, v177
	v_add_f32_e32 v219, v179, v219
	v_add_f32_e32 v219, v254, v219
	v_cvt_pk_fp8_f32 v251, v179, v254 op_sel:[0,0,1]
	v_exp_f32_e32 v0, v74
	v_exp_f32_e32 v177, v75
	v_exp_f32_e32 v179, v76
	v_exp_f32_e32 v254, v77
	v_add_f32_e32 v219, v0, v219
	v_add_f32_e32 v219, v177, v219
	v_cvt_pk_fp8_f32 v252, v0, v177
	v_add_f32_e32 v219, v179, v219
	v_add_f32_e32 v219, v254, v219
	v_cvt_pk_fp8_f32 v252, v179, v254 op_sel:[0,0,1]
	s_waitcnt lgkmcnt(2)
	v_mfma_scale_f32_32x32x64_f8f6f4 v[114:129], v[90:97], v[130:137], v[114:129], v194, v193 op_sel_hi:[0,0,0]
	v_exp_f32_e32 v0, v78
	v_exp_f32_e32 v177, v79
	v_exp_f32_e32 v179, v80
	v_exp_f32_e32 v254, v81
	v_add_f32_e32 v219, v0, v219
	v_add_f32_e32 v219, v177, v219
	v_cvt_pk_fp8_f32 v253, v0, v177
	v_add_f32_e32 v219, v179, v219
	v_add_f32_e32 v219, v254, v219
	v_cvt_pk_fp8_f32 v253, v179, v254 op_sel:[0,0,1]
	ds_read_b128 v[90:93], v185 offset:0
	ds_read_b128 v[94:97], v186 offset:0
	ds_read_b128 v[82:85], v185 offset:2048
	ds_read_b128 v[86:89], v186 offset:2048
	ds_read_b128 v[74:77], v185 offset:4096
	ds_read_b128 v[78:81], v186 offset:4096
	ds_read_b128 v[66:69], v185 offset:6144
	ds_read_b128 v[70:73], v186 offset:6144
	s_waitcnt lgkmcnt(8)
	v_mfma_scale_f32_32x32x64_f8f6f4 v[98:113], v[222:229], v[130:137], v[98:113], v194, v193 op_sel_hi:[0,0,0]
	v_mov_b32_e32 v0, v219
	s_nop 1
	v_permlane32_swap_b32_e32 v219, v0
	v_add_f32_e32 v219, v219, v0
	v_fma_f32 v209, v209, v218, v219
	v_max_f32_e32 v177, v114, v115
	v_max3_f32 v177, v177, v116, v117
	v_max3_f32 v177, v177, v118, v119
	v_max3_f32 v177, v177, v120, v121
	v_max3_f32 v177, v177, v122, v123
	v_max3_f32 v177, v177, v124, v125
	v_max3_f32 v177, v177, v126, v127
	v_max3_f32 v177, v177, v128, v129
	s_waitcnt lgkmcnt(6)
	v_mfma_scale_f32_32x32x64_f8f6f4 v[50:65], v[246:253], v[90:97], v[50:65], v194, v194 op_sel_hi:[0,0,0]
	s_waitcnt lgkmcnt(4)
	v_mfma_scale_f32_32x32x64_f8f6f4 v[34:49], v[246:253], v[82:89], v[34:49], v194, v194 op_sel_hi:[0,0,0]
	s_waitcnt vmcnt(0)
	ds_write_b128 v210, v[158:161] offset:43008
	ds_write_b128 v211, v[162:165] offset:51200
	ds_write_b128 v212, v[154:157] offset:59392
	s_waitcnt lgkmcnt(5)
	v_mfma_scale_f32_32x32x64_f8f6f4 v[18:33], v[246:253], v[74:81], v[18:33], v194, v194 op_sel_hi:[0,0,0]
	s_waitcnt lgkmcnt(0)
	s_barrier
	s_waitcnt lgkmcnt(0)
	v_mfma_scale_f32_32x32x64_f8f6f4 v[2:17], v[246:253], v[66:73], v[2:17], v194, v194 op_sel_hi:[0,0,0]
	v_max_f32_e32 v0, v98, v99
	v_max3_f32 v0, v0, v100, v101
	v_max3_f32 v0, v0, v102, v103
	v_max3_f32 v0, v0, v104, v105
	v_max3_f32 v0, v0, v106, v107
	v_max3_f32 v0, v0, v108, v109
	v_max3_f32 v0, v0, v110, v111
	v_max3_f32 v0, v0, v112, v113
	v_max_f32_e32 v177, v177, v0
	v_mov_b32_e32 v0, v177
	v_mov_b32_e32 v221, 1.0
	s_nop 0
	v_permlane32_swap_b32_e32 v177, v0
	v_max_f32_e32 v177, v177, v0
	v_cmp_ge_f32_e32 vcc, s90, v177
	s_cmp_eq_u64 vcc, exec
	s_cbranch_scc0 .Lmla_h0_newmax
; __device__ __forceinline__ void finishSM9(f32x16& p0, f32x16& p1, float alpha, float& l_reg, v8i32& p8) {
; #pragma unroll
;   for (int r = 0; r < 16; ++r) { p0[r] = __builtin_amdgcn_exp2f(p0[r]); p1[r] = __builtin_amdgcn_exp2f(p1[r]); }
;   float ps = 0;
; #pragma unroll
;   for (int r = 0; r < 16; ++r) ps += p0[r];
; #pragma unroll
;   for (int r = 0; r < 16; ++r) ps += p1[r];
;   { auto rr = __builtin_amdgcn_permlane32_swap(__float_as_uint(ps), __float_as_uint(ps), false, false);
;     ps = __uint_as_float(rr[0]) + __uint_as_float(rr[1]); }
;   l_reg = l_reg * alpha + ps;
; #pragma unroll
;   for (int g = 0; g < 4; ++g) {
;     int w = __builtin_amdgcn_cvt_pk_fp8_f32(p0[4 * g], p0[4 * g + 1], 0, false); p8[g] = __builtin_amdgcn_cvt_pk_fp8_f32(p0[4 * g + 2], p0[4 * g + 3], w, true);
;     int u = __builtin_amdgcn_cvt_pk_fp8_f32(p1[4 * g], p1[4 * g + 1], 0, false); p8[4 + g] = __builtin_amdgcn_cvt_pk_fp8_f32(p1[4 * g + 2], p1[4 * g + 3], u, true); }
; }
; __device__ __forceinline__ void pv8(f32x16* o, const char* Vt, const v8i32 p8, int r32, int hi) {
;   const int sw = (r32 >> 2) & 3, a0 = r32 * 64 + (((hi * 2) ^ sw) << 4), a1 = r32 * 64 + (((hi * 2 + 1) ^ sw) << 4);
; #pragma unroll
;   for (int d0 = 0; d0 < 4; ++d0) {
;     const v8i32 vf = cat8(*reinterpret_cast<const v4i32*>(Vt + d0 * 2048 + a0), *reinterpret_cast<const v4i32*>(Vt + d0 * 2048 + a1));
;     o[d0] = __builtin_amdgcn_mfma_scale_f32_32x32x64_f8f6f4(p8, vf, o[d0], 0, 0, 0, 127, 0, 127); }
; }
; __device__ __forceinline__ void qkt9(f32x16& p0, f32x16& p1, const char* Kn, const char* Kr, const v8i32* qf, const float init, int r32, int hi) {
; #pragma unroll
;   for (int r = 0; r < 16; ++r) { p0[r] = init; p1[r] = init; }
; #pragma unroll
;   for (int s = 0; s < 2; ++s) { const int c0 = s * 4 + hi * 2;
;     const v8i32 a0 = cat8(*reinterpret_cast<const v4i32*>(Kn + KN8SW(r32, c0)), *reinterpret_cast<const v4i32*>(Kn + KN8SW(r32, c0 + 1)));
;     const v8i32 a1 = cat8(*reinterpret_cast<const v4i32*>(Kn + 4096 + KN8SW(r32, c0)), *reinterpret_cast<const v4i32*>(Kn + 4096 + KN8SW(r32, c0 + 1)));
;     p0 = __builtin_amdgcn_mfma_scale_f32_32x32x64_f8f6f4(a0, qf[s], p0, 0, 0, 0, 127, 0, 124);
;     p1 = __builtin_amdgcn_mfma_scale_f32_32x32x64_f8f6f4(a1, qf[s], p1, 0, 0, 0, 127, 0, 124); }
;   { const int c0 = hi * 2;
.Lmla_h0_cont:
	global_load_dwordx4 v[158:161], v176, s[18:19]
	global_load_dwordx4 v[162:165], v178, s[16:17]
	global_load_dwordx4 v[154:157], v[180:181], off
	ds_read_b128 v[82:85], v215 offset:51200
	ds_read_b128 v[86:89], v216 offset:51200
	ds_read_b128 v[222:225], v215 offset:55296
	ds_read_b128 v[226:229], v216 offset:55296
	v_add_u32_e32 v176, 0x2000, v176
	v_add_u32_e32 v178, 0x20000, v178
	s_mov_b64 s[20:21], 0x1000
	v_lshl_add_u64 v[180:181], v[180:181], 0, s[20:21]
	v_exp_f32_e32 v0, v114
	v_exp_f32_e32 v177, v115
	v_exp_f32_e32 v179, v116
	v_exp_f32_e32 v254, v117
	v_add_f32_e32 v219, v0, v177
	v_cvt_pk_fp8_f32 v246, v0, v177
	v_add_f32_e32 v219, v179, v219
	v_add_f32_e32 v219, v254, v219
	v_cvt_pk_fp8_f32 v246, v179, v254 op_sel:[0,0,1]
	s_waitcnt lgkmcnt(2)
	v_mfma_scale_f32_32x32x64_f8f6f4 v[82:97], v[82:89], v[146:153], v[230:245], v194, v193 op_sel_hi:[0,0,0]
	v_exp_f32_e32 v0, v118
	v_exp_f32_e32 v177, v119
	v_exp_f32_e32 v179, v120
	v_exp_f32_e32 v254, v121
	v_add_f32_e32 v219, v0, v219
	v_add_f32_e32 v219, v177, v219
	v_cvt_pk_fp8_f32 v247, v0, v177
	v_add_f32_e32 v219, v179, v219
	v_add_f32_e32 v219, v254, v219
	v_cvt_pk_fp8_f32 v247, v179, v254 op_sel:[0,0,1]
	ds_read_b128 v[114:117], v213 offset:51200
	ds_read_b128 v[118:121], v214 offset:51200
	s_waitcnt lgkmcnt(2)
	v_mfma_scale_f32_32x32x64_f8f6f4 v[66:81], v[222:229], v[146:153], v[230:245], v194, v193 op_sel_hi:[0,0,0]
	ds_read_b128 v[222:225], v213 offset:55296
	ds_read_b128 v[226:229], v214 offset:55296
	v_exp_f32_e32 v0, v122
	v_exp_f32_e32 v177, v123
	v_exp_f32_e32 v179, v124
	v_exp_f32_e32 v254, v125
	v_add_f32_e32 v219, v0, v219
	v_add_f32_e32 v219, v177, v219
	v_cvt_pk_fp8_f32 v248, v0, v177
	v_add_f32_e32 v219, v179, v219
	v_add_f32_e32 v219, v254, v219
	v_cvt_pk_fp8_f32 v248, v179, v254 op_sel:[0,0,1]
	v_exp_f32_e32 v0, v126
	v_exp_f32_e32 v177, v127
	v_exp_f32_e32 v179, v128
	v_exp_f32_e32 v254, v129
	v_add_f32_e32 v219, v0, v219
	v_add_f32_e32 v219, v177, v219
	v_cvt_pk_fp8_f32 v249, v0, v177
	v_add_f32_e32 v219, v179, v219
	v_add_f32_e32 v219, v254, v219
	v_cvt_pk_fp8_f32 v249, v179, v254 op_sel:[0,0,1]
	ds_read_b128 v[122:125], v185 offset:59392
	ds_read_b128 v[126:129], v186 offset:59392
	s_waitcnt lgkmcnt(4)
	v_mfma_scale_f32_32x32x64_f8f6f4 v[82:97], v[114:121], v[138:145], v[82:97], v194, v193 op_sel_hi:[0,0,0]
	v_exp_f32_e32 v0, v98
	v_exp_f32_e32 v177, v99
	v_exp_f32_e32 v179, v100
	v_exp_f32_e32 v254, v101
	v_add_f32_e32 v219, v0, v219
	v_add_f32_e32 v219, v177, v219
	v_cvt_pk_fp8_f32 v250, v0, v177
	v_add_f32_e32 v219, v179, v219
	v_add_f32_e32 v219, v254, v219
	v_cvt_pk_fp8_f32 v250, v179, v254 op_sel:[0,0,1]
	s_waitcnt lgkmcnt(2)
	v_mfma_scale_f32_32x32x64_f8f6f4 v[66:81], v[222:229], v[138:145], v[66:81], v194, v193 op_sel_hi:[0,0,0]
	ds_read_b128 v[222:225], v185 offset:61440
	ds_read_b128 v[226:229], v186 offset:61440
	v_exp_f32_e32 v0, v102
	v_exp_f32_e32 v177, v103
	v_exp_f32_e32 v179, v104
	v_exp_f32_e32 v254, v105
	v_add_f32_e32 v219, v0, v219
	v_add_f32_e32 v219, v177, v219
	v_cvt_pk_fp8_f32 v251, v0, v177
	v_add_f32_e32 v219, v179, v219
	v_add_f32_e32 v219, v254, v219
	v_cvt_pk_fp8_f32 v251, v179, v254 op_sel:[0,0,1]
	v_exp_f32_e32 v0, v106
	v_exp_f32_e32 v177, v107
	v_exp_f32_e32 v179, v108
	v_exp_f32_e32 v254, v109
	v_add_f32_e32 v219, v0, v219
	v_add_f32_e32 v219, v177, v219
	v_cvt_pk_fp8_f32 v252, v0, v177
	v_add_f32_e32 v219, v179, v219
	v_add_f32_e32 v219, v254, v219
	v_cvt_pk_fp8_f32 v252, v179, v254 op_sel:[0,0,1]
	s_waitcnt lgkmcnt(2)
	v_mfma_scale_f32_32x32x64_f8f6f4 v[82:97], v[122:129], v[130:137], v[82:97], v194, v193 op_sel_hi:[0,0,0]
	v_exp_f32_e32 v0, v110
	v_exp_f32_e32 v177, v111
	v_exp_f32_e32 v179, v112
	v_exp_f32_e32 v254, v113
	v_add_f32_e32 v219, v0, v219
	v_add_f32_e32 v219, v177, v219
	v_cvt_pk_fp8_f32 v253, v0, v177
	v_add_f32_e32 v219, v179, v219
	v_add_f32_e32 v219, v254, v219
	v_cvt_pk_fp8_f32 v253, v179, v254 op_sel:[0,0,1]
	ds_read_b128 v[122:125], v185 offset:8192
	ds_read_b128 v[126:129], v186 offset:8192
	ds_read_b128 v[114:117], v185 offset:10240
	ds_read_b128 v[118:121], v186 offset:10240
	ds_read_b128 v[106:109], v185 offset:12288
	ds_read_b128 v[110:113], v186 offset:12288
	ds_read_b128 v[98:101], v185 offset:14336
	ds_read_b128 v[102:105], v186 offset:14336
	s_waitcnt lgkmcnt(8)
	v_mfma_scale_f32_32x32x64_f8f6f4 v[66:81], v[222:229], v[130:137], v[66:81], v194, v193 op_sel_hi:[0,0,0]
	v_mov_b32_e32 v0, v219
	s_nop 1
	v_permlane32_swap_b32_e32 v219, v0
	v_add_f32_e32 v219, v219, v0
	v_fma_f32 v209, v209, v221, v219
	v_max_f32_e32 v177, v82, v83
	v_max3_f32 v177, v177, v84, v85
	v_max3_f32 v177, v177, v86, v87
	v_max3_f32 v177, v177, v88, v89
	v_max3_f32 v177, v177, v90, v91
	v_max3_f32 v177, v177, v92, v93
	v_max3_f32 v177, v177, v94, v95
	v_max3_f32 v177, v177, v96, v97
	s_waitcnt lgkmcnt(6)
	v_mfma_scale_f32_32x32x64_f8f6f4 v[50:65], v[246:253], v[122:129], v[50:65], v194, v194 op_sel_hi:[0,0,0]
	s_waitcnt lgkmcnt(4)
	v_mfma_scale_f32_32x32x64_f8f6f4 v[34:49], v[246:253], v[114:121], v[34:49], v194, v194 op_sel_hi:[0,0,0]
	s_waitcnt vmcnt(0)
	ds_write_b128 v210, v[158:161]
	ds_write_b128 v211, v[162:165] offset:16384
	ds_write_b128 v212, v[154:157] offset:32768
	s_waitcnt lgkmcnt(5)
	v_mfma_scale_f32_32x32x64_f8f6f4 v[18:33], v[246:253], v[106:113], v[18:33], v194, v194 op_sel_hi:[0,0,0]
	s_waitcnt lgkmcnt(0)
	s_barrier
	s_waitcnt lgkmcnt(0)
	v_mfma_scale_f32_32x32x64_f8f6f4 v[2:17], v[246:253], v[98:105], v[2:17], v194, v194 op_sel_hi:[0,0,0]
	v_max_f32_e32 v0, v66, v67
	v_max3_f32 v0, v0, v68, v69
	v_max3_f32 v0, v0, v70, v71
	v_max3_f32 v0, v0, v72, v73
	v_max3_f32 v0, v0, v74, v75
	v_max3_f32 v0, v0, v76, v77
	v_max3_f32 v0, v0, v78, v79
	v_max3_f32 v0, v0, v80, v81
	v_max_f32_e32 v177, v177, v0
	v_mov_b32_e32 v0, v177
	v_mov_b32_e32 v218, 1.0
	s_nop 0
	v_permlane32_swap_b32_e32 v177, v0
	v_max_f32_e32 v177, v177, v0
	v_cmp_ge_f32_e32 vcc, s90, v177
	s_cmp_eq_u64 vcc, exec
	s_cbranch_scc0 .Lmla_h1_newmax
; __device__ __forceinline__ void finishSM9(f32x16& p0, f32x16& p1, float alpha, float& l_reg, v8i32& p8) {
; #pragma unroll
;   for (int r = 0; r < 16; ++r) { p0[r] = __builtin_amdgcn_exp2f(p0[r]); p1[r] = __builtin_amdgcn_exp2f(p1[r]); }
;   float ps = 0;
; #pragma unroll
;   for (int r = 0; r < 16; ++r) ps += p0[r];
; #pragma unroll
;   for (int r = 0; r < 16; ++r) ps += p1[r];
;   { auto rr = __builtin_amdgcn_permlane32_swap(__float_as_uint(ps), __float_as_uint(ps), false, false);
;     ps = __uint_as_float(rr[0]) + __uint_as_float(rr[1]); }
;   l_reg = l_reg * alpha + ps;
; #pragma unroll
;   for (int g = 0; g < 4; ++g) {
;     int w = __builtin_amdgcn_cvt_pk_fp8_f32(p0[4 * g], p0[4 * g + 1], 0, false); p8[g] = __builtin_amdgcn_cvt_pk_fp8_f32(p0[4 * g + 2], p0[4 * g + 3], w, true);
;     int u = __builtin_amdgcn_cvt_pk_fp8_f32(p1[4 * g], p1[4 * g + 1], 0, false); p8[4 + g] = __builtin_amdgcn_cvt_pk_fp8_f32(p1[4 * g + 2], p1[4 * g + 3], u, true); }
; }
; __device__ __forceinline__ void pv8(f32x16* o, const char* Vt, const v8i32 p8, int r32, int hi) {
;   const int sw = (r32 >> 2) & 3, a0 = r32 * 64 + (((hi * 2) ^ sw) << 4), a1 = r32 * 64 + (((hi * 2 + 1) ^ sw) << 4);
; #pragma unroll
;   for (int d0 = 0; d0 < 4; ++d0) {
;     const v8i32 vf = cat8(*reinterpret_cast<const v4i32*>(Vt + d0 * 2048 + a0), *reinterpret_cast<const v4i32*>(Vt + d0 * 2048 + a1));
;     o[d0] = __builtin_amdgcn_mfma_scale_f32_32x32x64_f8f6f4(p8, vf, o[d0], 0, 0, 0, 127, 0, 127); }
; }
; __device__ __forceinline__ void qkt9(f32x16& p0, f32x16& p1, const char* Kn, const char* Kr, const v8i32* qf, const float init, int r32, int hi) {
; #pragma unroll
;   for (int r = 0; r < 16; ++r) { p0[r] = init; p1[r] = init; }
; #pragma unroll
;   for (int s = 0; s < 2; ++s) { const int c0 = s * 4 + hi * 2;
;     const v8i32 a0 = cat8(*reinterpret_cast<const v4i32*>(Kn + KN8SW(r32, c0)), *reinterpret_cast<const v4i32*>(Kn + KN8SW(r32, c0 + 1)));
;     const v8i32 a1 = cat8(*reinterpret_cast<const v4i32*>(Kn + 4096 + KN8SW(r32, c0)), *reinterpret_cast<const v4i32*>(Kn + 4096 + KN8SW(r32, c0 + 1)));
;     p0 = __builtin_amdgcn_mfma_scale_f32_32x32x64_f8f6f4(a0, qf[s], p0, 0, 0, 0, 127, 0, 124);
;     p1 = __builtin_amdgcn_mfma_scale_f32_32x32x64_f8f6f4(a1, qf[s], p1, 0, 0, 0, 127, 0, 124); }
;   { const int c0 = hi * 2;
.Lmla_h1_cont:
	global_load_dwordx4 v[158:161], v176, s[18:19]
	global_load_dwordx4 v[162:165], v178, s[16:17]
	global_load_dwordx4 v[154:157], v[180:181], off
	ds_read_b128 v[114:117], v215 offset:16384
	ds_read_b128 v[118:121], v216 offset:16384
	ds_read_b128 v[222:225], v215 offset:20480
	ds_read_b128 v[226:229], v216 offset:20480
	v_add_u32_e32 v176, 0x2000, v176
	v_add_u32_e32 v178, 0x20000, v178
	s_mov_b64 s[20:21], 0x1000
	v_lshl_add_u64 v[180:181], v[180:181], 0, s[20:21]
	v_exp_f32_e32 v0, v82
	v_exp_f32_e32 v177, v83
	v_exp_f32_e32 v179, v84
	v_exp_f32_e32 v254, v85
	v_add_f32_e32 v219, v0, v177
	v_cvt_pk_fp8_f32 v246, v0, v177
	v_add_f32_e32 v219, v179, v219
	v_add_f32_e32 v219, v254, v219
	v_cvt_pk_fp8_f32 v246, v179, v254 op_sel:[0,0,1]
	s_waitcnt lgkmcnt(2)
	v_mfma_scale_f32_32x32x64_f8f6f4 v[114:129], v[114:121], v[146:153], v[230:245], v194, v193 op_sel_hi:[0,0,0]
	v_exp_f32_e32 v0, v86
	v_exp_f32_e32 v177, v87
	v_exp_f32_e32 v179, v88
	v_exp_f32_e32 v254, v89
	v_add_f32_e32 v219, v0, v219
	v_add_f32_e32 v219, v177, v219
	v_cvt_pk_fp8_f32 v247, v0, v177
	v_add_f32_e32 v219, v179, v219
	v_add_f32_e32 v219, v254, v219
	v_cvt_pk_fp8_f32 v247, v179, v254 op_sel:[0,0,1]
	ds_read_b128 v[82:85], v213 offset:16384
	ds_read_b128 v[86:89], v214 offset:16384
	s_waitcnt lgkmcnt(2)
	v_mfma_scale_f32_32x32x64_f8f6f4 v[98:113], v[222:229], v[146:153], v[230:245], v194, v193 op_sel_hi:[0,0,0]
	ds_read_b128 v[222:225], v213 offset:20480
	ds_read_b128 v[226:229], v214 offset:20480
	v_exp_f32_e32 v0, v90
	v_exp_f32_e32 v177, v91
	v_exp_f32_e32 v179, v92
	v_exp_f32_e32 v254, v93
	v_add_f32_e32 v219, v0, v219
	v_add_f32_e32 v219, v177, v219
	v_cvt_pk_fp8_f32 v248, v0, v177
	v_add_f32_e32 v219, v179, v219
	v_add_f32_e32 v219, v254, v219
	v_cvt_pk_fp8_f32 v248, v179, v254 op_sel:[0,0,1]
	v_exp_f32_e32 v0, v94
	v_exp_f32_e32 v177, v95
	v_exp_f32_e32 v179, v96
	v_exp_f32_e32 v254, v97
	v_add_f32_e32 v219, v0, v219
	v_add_f32_e32 v219, v177, v219
	v_cvt_pk_fp8_f32 v249, v0, v177
	v_add_f32_e32 v219, v179, v219
	v_add_f32_e32 v219, v254, v219
	v_cvt_pk_fp8_f32 v249, v179, v254 op_sel:[0,0,1]
	ds_read_b128 v[90:93], v185 offset:32768
	ds_read_b128 v[94:97], v186 offset:32768
	s_waitcnt lgkmcnt(4)
	v_mfma_scale_f32_32x32x64_f8f6f4 v[114:129], v[82:89], v[138:145], v[114:129], v194, v193 op_sel_hi:[0,0,0]
	v_exp_f32_e32 v0, v66
	v_exp_f32_e32 v177, v67
	v_exp_f32_e32 v179, v68
	v_exp_f32_e32 v254, v69
	v_add_f32_e32 v219, v0, v219
	v_add_f32_e32 v219, v177, v219
	v_cvt_pk_fp8_f32 v250, v0, v177
	v_add_f32_e32 v219, v179, v219
	v_add_f32_e32 v219, v254, v219
	v_cvt_pk_fp8_f32 v250, v179, v254 op_sel:[0,0,1]
	s_waitcnt lgkmcnt(2)
	v_mfma_scale_f32_32x32x64_f8f6f4 v[98:113], v[222:229], v[138:145], v[98:113], v194, v193 op_sel_hi:[0,0,0]
	ds_read_b128 v[222:225], v185 offset:34816
	ds_read_b128 v[226:229], v186 offset:34816
	v_exp_f32_e32 v0, v70
	v_exp_f32_e32 v177, v71
	v_exp_f32_e32 v179, v72
	v_exp_f32_e32 v254, v73
	v_add_f32_e32 v219, v0, v219
	v_add_f32_e32 v219, v177, v219
	v_cvt_pk_fp8_f32 v251, v0, v177
	v_add_f32_e32 v219, v179, v219
	v_add_f32_e32 v219, v254, v219
	v_cvt_pk_fp8_f32 v251, v179, v254 op_sel:[0,0,1]
	v_exp_f32_e32 v0, v74
	v_exp_f32_e32 v177, v75
	v_exp_f32_e32 v179, v76
	v_exp_f32_e32 v254, v77
	v_add_f32_e32 v219, v0, v219
	v_add_f32_e32 v219, v177, v219
	v_cvt_pk_fp8_f32 v252, v0, v177
	v_add_f32_e32 v219, v179, v219
	v_add_f32_e32 v219, v254, v219
	v_cvt_pk_fp8_f32 v252, v179, v254 op_sel:[0,0,1]
	s_waitcnt lgkmcnt(2)
	v_mfma_scale_f32_32x32x64_f8f6f4 v[114:129], v[90:97], v[130:137], v[114:129], v194, v193 op_sel_hi:[0,0,0]
	v_exp_f32_e32 v0, v78
	v_exp_f32_e32 v177, v79
	v_exp_f32_e32 v179, v80
	v_exp_f32_e32 v254, v81
	v_add_f32_e32 v219, v0, v219
	v_add_f32_e32 v219, v177, v219
	v_cvt_pk_fp8_f32 v253, v0, v177
	v_add_f32_e32 v219, v179, v219
	v_add_f32_e32 v219, v254, v219
	v_cvt_pk_fp8_f32 v253, v179, v254 op_sel:[0,0,1]
	ds_read_b128 v[90:93], v185 offset:43008
	ds_read_b128 v[94:97], v186 offset:43008
	ds_read_b128 v[82:85], v185 offset:45056
	ds_read_b128 v[86:89], v186 offset:45056
	ds_read_b128 v[74:77], v185 offset:47104
	ds_read_b128 v[78:81], v186 offset:47104
	ds_read_b128 v[66:69], v185 offset:49152
	ds_read_b128 v[70:73], v186 offset:49152
	s_waitcnt lgkmcnt(8)
	v_mfma_scale_f32_32x32x64_f8f6f4 v[98:113], v[222:229], v[130:137], v[98:113], v194, v193 op_sel_hi:[0,0,0]
	v_mov_b32_e32 v0, v219
	s_nop 1
	v_permlane32_swap_b32_e32 v219, v0
	v_add_f32_e32 v219, v219, v0
	v_fma_f32 v209, v209, v218, v219
	v_max_f32_e32 v177, v114, v115
	v_max3_f32 v177, v177, v116, v117
	v_max3_f32 v177, v177, v118, v119
	v_max3_f32 v177, v177, v120, v121
	v_max3_f32 v177, v177, v122, v123
	v_max3_f32 v177, v177, v124, v125
	v_max3_f32 v177, v177, v126, v127
	v_max3_f32 v177, v177, v128, v129
	s_waitcnt lgkmcnt(6)
	v_mfma_scale_f32_32x32x64_f8f6f4 v[50:65], v[246:253], v[90:97], v[50:65], v194, v194 op_sel_hi:[0,0,0]
	s_waitcnt lgkmcnt(4)
	v_mfma_scale_f32_32x32x64_f8f6f4 v[34:49], v[246:253], v[82:89], v[34:49], v194, v194 op_sel_hi:[0,0,0]
	s_waitcnt vmcnt(0)
	ds_write_b128 v210, v[158:161] offset:8192
	ds_write_b128 v211, v[162:165] offset:24576
	ds_write_b128 v212, v[154:157] offset:36864
	s_waitcnt lgkmcnt(5)
	v_mfma_scale_f32_32x32x64_f8f6f4 v[18:33], v[246:253], v[74:81], v[18:33], v194, v194 op_sel_hi:[0,0,0]
	s_waitcnt lgkmcnt(0)
	s_barrier
	s_waitcnt lgkmcnt(0)
	v_mfma_scale_f32_32x32x64_f8f6f4 v[2:17], v[246:253], v[66:73], v[2:17], v194, v194 op_sel_hi:[0,0,0]
	v_max_f32_e32 v0, v98, v99
	v_max3_f32 v0, v0, v100, v101
	v_max3_f32 v0, v0, v102, v103
	v_max3_f32 v0, v0, v104, v105
	v_max3_f32 v0, v0, v106, v107
	v_max3_f32 v0, v0, v108, v109
	v_max3_f32 v0, v0, v110, v111
	v_max3_f32 v0, v0, v112, v113
	v_max_f32_e32 v177, v177, v0
	v_mov_b32_e32 v0, v177
	v_mov_b32_e32 v221, 1.0
	s_nop 0
	v_permlane32_swap_b32_e32 v177, v0
	v_max_f32_e32 v177, v177, v0
	v_cmp_ge_f32_e32 vcc, s90, v177
	s_cmp_eq_u64 vcc, exec
	s_cbranch_scc0 .Lmla_h2_newmax
; __device__ __forceinline__ void finishSM9(f32x16& p0, f32x16& p1, float alpha, float& l_reg, v8i32& p8) {
; #pragma unroll
;   for (int r = 0; r < 16; ++r) { p0[r] = __builtin_amdgcn_exp2f(p0[r]); p1[r] = __builtin_amdgcn_exp2f(p1[r]); }
;   float ps = 0;
; #pragma unroll
;   for (int r = 0; r < 16; ++r) ps += p0[r];
; #pragma unroll
;   for (int r = 0; r < 16; ++r) ps += p1[r];
;   { auto rr = __builtin_amdgcn_permlane32_swap(__float_as_uint(ps), __float_as_uint(ps), false, false);
;     ps = __uint_as_float(rr[0]) + __uint_as_float(rr[1]); }
;   l_reg = l_reg * alpha + ps;
; #pragma unroll
;   for (int g = 0; g < 4; ++g) {
;     int w = __builtin_amdgcn_cvt_pk_fp8_f32(p0[4 * g], p0[4 * g + 1], 0, false); p8[g] = __builtin_amdgcn_cvt_pk_fp8_f32(p0[4 * g + 2], p0[4 * g + 3], w, true);
;     int u = __builtin_amdgcn_cvt_pk_fp8_f32(p1[4 * g], p1[4 * g + 1], 0, false); p8[4 + g] = __builtin_amdgcn_cvt_pk_fp8_f32(p1[4 * g + 2], p1[4 * g + 3], u, true); }
; }
; __device__ __forceinline__ void pv8(f32x16* o, const char* Vt, const v8i32 p8, int r32, int hi) {
;   const int sw = (r32 >> 2) & 3, a0 = r32 * 64 + (((hi * 2) ^ sw) << 4), a1 = r32 * 64 + (((hi * 2 + 1) ^ sw) << 4);
; #pragma unroll
;   for (int d0 = 0; d0 < 4; ++d0) {
;     const v8i32 vf = cat8(*reinterpret_cast<const v4i32*>(Vt + d0 * 2048 + a0), *reinterpret_cast<const v4i32*>(Vt + d0 * 2048 + a1));
;     o[d0] = __builtin_amdgcn_mfma_scale_f32_32x32x64_f8f6f4(p8, vf, o[d0], 0, 0, 0, 127, 0, 127); }
; }
; __device__ __forceinline__ void qkt9(f32x16& p0, f32x16& p1, const char* Kn, const char* Kr, const v8i32* qf, const float init, int r32, int hi) {
; #pragma unroll
;   for (int r = 0; r < 16; ++r) { p0[r] = init; p1[r] = init; }
; #pragma unroll
;   for (int s = 0; s < 2; ++s) { const int c0 = s * 4 + hi * 2;
;     const v8i32 a0 = cat8(*reinterpret_cast<const v4i32*>(Kn + KN8SW(r32, c0)), *reinterpret_cast<const v4i32*>(Kn + KN8SW(r32, c0 + 1)));
;     const v8i32 a1 = cat8(*reinterpret_cast<const v4i32*>(Kn + 4096 + KN8SW(r32, c0)), *reinterpret_cast<const v4i32*>(Kn + 4096 + KN8SW(r32, c0 + 1)));
;     p0 = __builtin_amdgcn_mfma_scale_f32_32x32x64_f8f6f4(a0, qf[s], p0, 0, 0, 0, 127, 0, 124);
;     p1 = __builtin_amdgcn_mfma_scale_f32_32x32x64_f8f6f4(a1, qf[s], p1, 0, 0, 0, 127, 0, 124); }
;   { const int c0 = hi * 2;
.Lmla_h2_cont:
	global_load_dwordx4 v[158:161], v176, s[18:19]
	global_load_dwordx4 v[162:165], v178, s[16:17]
	global_load_dwordx4 v[154:157], v[180:181], off
	ds_read_b128 v[82:85], v215 offset:24576
	ds_read_b128 v[86:89], v216 offset:24576
	ds_read_b128 v[222:225], v215 offset:28672
	ds_read_b128 v[226:229], v216 offset:28672
	v_add_u32_e32 v176, 0x2000, v176
	v_add_u32_e32 v178, 0x20000, v178
	s_mov_b64 s[20:21], 0x1000
	v_lshl_add_u64 v[180:181], v[180:181], 0, s[20:21]
	v_exp_f32_e32 v0, v114
	v_exp_f32_e32 v177, v115
	v_exp_f32_e32 v179, v116
	v_exp_f32_e32 v254, v117
	v_add_f32_e32 v219, v0, v177
	v_cvt_pk_fp8_f32 v246, v0, v177
	v_add_f32_e32 v219, v179, v219
	v_add_f32_e32 v219, v254, v219
	v_cvt_pk_fp8_f32 v246, v179, v254 op_sel:[0,0,1]
	s_waitcnt lgkmcnt(2)
	v_mfma_scale_f32_32x32x64_f8f6f4 v[82:97], v[82:89], v[146:153], v[230:245], v194, v193 op_sel_hi:[0,0,0]
	v_exp_f32_e32 v0, v118
	v_exp_f32_e32 v177, v119
	v_exp_f32_e32 v179, v120
	v_exp_f32_e32 v254, v121
	v_add_f32_e32 v219, v0, v219
	v_add_f32_e32 v219, v177, v219
	v_cvt_pk_fp8_f32 v247, v0, v177
	v_add_f32_e32 v219, v179, v219
	v_add_f32_e32 v219, v254, v219
	v_cvt_pk_fp8_f32 v247, v179, v254 op_sel:[0,0,1]
	ds_read_b128 v[114:117], v213 offset:24576
	ds_read_b128 v[118:121], v214 offset:24576
	s_waitcnt lgkmcnt(2)
	v_mfma_scale_f32_32x32x64_f8f6f4 v[66:81], v[222:229], v[146:153], v[230:245], v194, v193 op_sel_hi:[0,0,0]
	ds_read_b128 v[222:225], v213 offset:28672
	ds_read_b128 v[226:229], v214 offset:28672
	v_exp_f32_e32 v0, v122
	v_exp_f32_e32 v177, v123
	v_exp_f32_e32 v179, v124
	v_exp_f32_e32 v254, v125
	v_add_f32_e32 v219, v0, v219
	v_add_f32_e32 v219, v177, v219
	v_cvt_pk_fp8_f32 v248, v0, v177
	v_add_f32_e32 v219, v179, v219
	v_add_f32_e32 v219, v254, v219
	v_cvt_pk_fp8_f32 v248, v179, v254 op_sel:[0,0,1]
	v_exp_f32_e32 v0, v126
	v_exp_f32_e32 v177, v127
	v_exp_f32_e32 v179, v128
	v_exp_f32_e32 v254, v129
	v_add_f32_e32 v219, v0, v219
	v_add_f32_e32 v219, v177, v219
	v_cvt_pk_fp8_f32 v249, v0, v177
	v_add_f32_e32 v219, v179, v219
	v_add_f32_e32 v219, v254, v219
	v_cvt_pk_fp8_f32 v249, v179, v254 op_sel:[0,0,1]
	ds_read_b128 v[122:125], v185 offset:36864
	ds_read_b128 v[126:129], v186 offset:36864
	s_waitcnt lgkmcnt(4)
	v_mfma_scale_f32_32x32x64_f8f6f4 v[82:97], v[114:121], v[138:145], v[82:97], v194, v193 op_sel_hi:[0,0,0]
	v_exp_f32_e32 v0, v98
	v_exp_f32_e32 v177, v99
	v_exp_f32_e32 v179, v100
	v_exp_f32_e32 v254, v101
	v_add_f32_e32 v219, v0, v219
	v_add_f32_e32 v219, v177, v219
	v_cvt_pk_fp8_f32 v250, v0, v177
	v_add_f32_e32 v219, v179, v219
	v_add_f32_e32 v219, v254, v219
	v_cvt_pk_fp8_f32 v250, v179, v254 op_sel:[0,0,1]
	s_waitcnt lgkmcnt(2)
	v_mfma_scale_f32_32x32x64_f8f6f4 v[66:81], v[222:229], v[138:145], v[66:81], v194, v193 op_sel_hi:[0,0,0]
	ds_read_b128 v[222:225], v185 offset:38912
	ds_read_b128 v[226:229], v186 offset:38912
	v_exp_f32_e32 v0, v102
	v_exp_f32_e32 v177, v103
	v_exp_f32_e32 v179, v104
	v_exp_f32_e32 v254, v105
	v_add_f32_e32 v219, v0, v219
	v_add_f32_e32 v219, v177, v219
	v_cvt_pk_fp8_f32 v251, v0, v177
	v_add_f32_e32 v219, v179, v219
	v_add_f32_e32 v219, v254, v219
	v_cvt_pk_fp8_f32 v251, v179, v254 op_sel:[0,0,1]
	v_exp_f32_e32 v0, v106
	v_exp_f32_e32 v177, v107
	v_exp_f32_e32 v179, v108
	v_exp_f32_e32 v254, v109
	v_add_f32_e32 v219, v0, v219
	v_add_f32_e32 v219, v177, v219
	v_cvt_pk_fp8_f32 v252, v0, v177
	v_add_f32_e32 v219, v179, v219
	v_add_f32_e32 v219, v254, v219
	v_cvt_pk_fp8_f32 v252, v179, v254 op_sel:[0,0,1]
	s_waitcnt lgkmcnt(2)
	v_mfma_scale_f32_32x32x64_f8f6f4 v[82:97], v[122:129], v[130:137], v[82:97], v194, v193 op_sel_hi:[0,0,0]
	v_exp_f32_e32 v0, v110
	v_exp_f32_e32 v177, v111
	v_exp_f32_e32 v179, v112
	v_exp_f32_e32 v254, v113
	v_add_f32_e32 v219, v0, v219
	v_add_f32_e32 v219, v177, v219
	v_cvt_pk_fp8_f32 v253, v0, v177
	v_add_f32_e32 v219, v179, v219
	v_add_f32_e32 v219, v254, v219
	v_cvt_pk_fp8_f32 v253, v179, v254 op_sel:[0,0,1]
	ds_read_b128 v[122:125], v185 offset:0
	ds_read_b128 v[126:129], v186 offset:0
	ds_read_b128 v[114:117], v185 offset:2048
	ds_read_b128 v[118:121], v186 offset:2048
	ds_read_b128 v[106:109], v185 offset:4096
	ds_read_b128 v[110:113], v186 offset:4096
	ds_read_b128 v[98:101], v185 offset:6144
	ds_read_b128 v[102:105], v186 offset:6144
	s_waitcnt lgkmcnt(8)
	v_mfma_scale_f32_32x32x64_f8f6f4 v[66:81], v[222:229], v[130:137], v[66:81], v194, v193 op_sel_hi:[0,0,0]
	v_mov_b32_e32 v0, v219
	s_nop 1
	v_permlane32_swap_b32_e32 v219, v0
	v_add_f32_e32 v219, v219, v0
	v_fma_f32 v209, v209, v221, v219
	v_max_f32_e32 v177, v82, v83
	v_max3_f32 v177, v177, v84, v85
	v_max3_f32 v177, v177, v86, v87
	v_max3_f32 v177, v177, v88, v89
	v_max3_f32 v177, v177, v90, v91
	v_max3_f32 v177, v177, v92, v93
	v_max3_f32 v177, v177, v94, v95
	v_max3_f32 v177, v177, v96, v97
	s_waitcnt lgkmcnt(6)
	v_mfma_scale_f32_32x32x64_f8f6f4 v[50:65], v[246:253], v[122:129], v[50:65], v194, v194 op_sel_hi:[0,0,0]
	s_waitcnt lgkmcnt(4)
	v_mfma_scale_f32_32x32x64_f8f6f4 v[34:49], v[246:253], v[114:121], v[34:49], v194, v194 op_sel_hi:[0,0,0]
	s_waitcnt vmcnt(0)
	ds_write_b128 v210, v[158:161] offset:43008
	ds_write_b128 v211, v[162:165] offset:51200
	ds_write_b128 v212, v[154:157] offset:59392
	s_waitcnt lgkmcnt(5)
	v_mfma_scale_f32_32x32x64_f8f6f4 v[18:33], v[246:253], v[106:113], v[18:33], v194, v194 op_sel_hi:[0,0,0]
	s_waitcnt lgkmcnt(0)
	s_barrier
	s_waitcnt lgkmcnt(0)
	v_mfma_scale_f32_32x32x64_f8f6f4 v[2:17], v[246:253], v[98:105], v[2:17], v194, v194 op_sel_hi:[0,0,0]
	v_max_f32_e32 v0, v66, v67
	v_max3_f32 v0, v0, v68, v69
	v_max3_f32 v0, v0, v70, v71
	v_max3_f32 v0, v0, v72, v73
	v_max3_f32 v0, v0, v74, v75
	v_max3_f32 v0, v0, v76, v77
	v_max3_f32 v0, v0, v78, v79
	v_max3_f32 v0, v0, v80, v81
	v_max_f32_e32 v177, v177, v0
	v_mov_b32_e32 v0, v177
	v_mov_b32_e32 v218, 1.0
	s_nop 0
	v_permlane32_swap_b32_e32 v177, v0
	v_max_f32_e32 v177, v177, v0
	v_cmp_ge_f32_e32 vcc, s90, v177
	s_cmp_eq_u64 vcc, exec
	s_cbranch_scc0 .Lmla_h3_newmax
; __device__ __forceinline__ void finishSM9(f32x16& p0, f32x16& p1, float alpha, float& l_reg, v8i32& p8) {
; #pragma unroll
;   for (int r = 0; r < 16; ++r) { p0[r] = __builtin_amdgcn_exp2f(p0[r]); p1[r] = __builtin_amdgcn_exp2f(p1[r]); }
;   float ps = 0;
; #pragma unroll
;   for (int r = 0; r < 16; ++r) ps += p0[r];
; #pragma unroll
;   for (int r = 0; r < 16; ++r) ps += p1[r];
;   { auto rr = __builtin_amdgcn_permlane32_swap(__float_as_uint(ps), __float_as_uint(ps), false, false);
;     ps = __uint_as_float(rr[0]) + __uint_as_float(rr[1]); }
;   l_reg = l_reg * alpha + ps;
; #pragma unroll
;   for (int g = 0; g < 4; ++g) {
;     int w = __builtin_amdgcn_cvt_pk_fp8_f32(p0[4 * g], p0[4 * g + 1], 0, false); p8[g] = __builtin_amdgcn_cvt_pk_fp8_f32(p0[4 * g + 2], p0[4 * g + 3], w, true);
;     int u = __builtin_amdgcn_cvt_pk_fp8_f32(p1[4 * g], p1[4 * g + 1], 0, false); p8[4 + g] = __builtin_amdgcn_cvt_pk_fp8_f32(p1[4 * g + 2], p1[4 * g + 3], u, true); }
; }
; __device__ __forceinline__ void pv8(f32x16* o, const char* Vt, const v8i32 p8, int r32, int hi) {
;   const int sw = (r32 >> 2) & 3, a0 = r32 * 64 + (((hi * 2) ^ sw) << 4), a1 = r32 * 64 + (((hi * 2 + 1) ^ sw) << 4);
; #pragma unroll
;   for (int d0 = 0; d0 < 4; ++d0) {
;     const v8i32 vf = cat8(*reinterpret_cast<const v4i32*>(Vt + d0 * 2048 + a0), *reinterpret_cast<const v4i32*>(Vt + d0 * 2048 + a1));
;     o[d0] = __builtin_amdgcn_mfma_scale_f32_32x32x64_f8f6f4(p8, vf, o[d0], 0, 0, 0, 127, 0, 127); }
; }
; __device__ __forceinline__ void qkt9(f32x16& p0, f32x16& p1, const char* Kn, const char* Kr, const v8i32* qf, const float init, int r32, int hi) {
; #pragma unroll
;   for (int r = 0; r < 16; ++r) { p0[r] = init; p1[r] = init; }
; #pragma unroll
;   for (int s = 0; s < 2; ++s) { const int c0 = s * 4 + hi * 2;
;     const v8i32 a0 = cat8(*reinterpret_cast<const v4i32*>(Kn + KN8SW(r32, c0)), *reinterpret_cast<const v4i32*>(Kn + KN8SW(r32, c0 + 1)));
;     const v8i32 a1 = cat8(*reinterpret_cast<const v4i32*>(Kn + 4096 + KN8SW(r32, c0)), *reinterpret_cast<const v4i32*>(Kn + 4096 + KN8SW(r32, c0 + 1)));
;     p0 = __builtin_amdgcn_mfma_scale_f32_32x32x64_f8f6f4(a0, qf[s], p0, 0, 0, 0, 127, 0, 124);
;     p1 = __builtin_amdgcn_mfma_scale_f32_32x32x64_f8f6f4(a1, qf[s], p1, 0, 0, 0, 127, 0, 124); }
;   { const int c0 = hi * 2;
.Lmla_h3_cont:
	global_load_dwordx4 v[158:161], v176, s[18:19]
	global_load_dwordx4 v[162:165], v178, s[16:17]
	global_load_dwordx4 v[154:157], v[180:181], off
	ds_read_b128 v[114:117], v215 offset:51200
	ds_read_b128 v[118:121], v216 offset:51200
	ds_read_b128 v[222:225], v215 offset:55296
	ds_read_b128 v[226:229], v216 offset:55296
	v_add_u32_e32 v176, 0x2000, v176
	v_add_u32_e32 v178, 0x20000, v178
	s_mov_b64 s[20:21], 0x1000
	v_lshl_add_u64 v[180:181], v[180:181], 0, s[20:21]
	v_exp_f32_e32 v0, v82
	v_exp_f32_e32 v177, v83
	v_exp_f32_e32 v179, v84
	v_exp_f32_e32 v254, v85
	v_add_f32_e32 v219, v0, v177
	v_cvt_pk_fp8_f32 v246, v0, v177
	v_add_f32_e32 v219, v179, v219
	v_add_f32_e32 v219, v254, v219
	v_cvt_pk_fp8_f32 v246, v179, v254 op_sel:[0,0,1]
	s_waitcnt lgkmcnt(2)
	v_mfma_scale_f32_32x32x64_f8f6f4 v[114:129], v[114:121], v[146:153], v[230:245], v194, v193 op_sel_hi:[0,0,0]
	v_exp_f32_e32 v0, v86
	v_exp_f32_e32 v177, v87
	v_exp_f32_e32 v179, v88
	v_exp_f32_e32 v254, v89
	v_add_f32_e32 v219, v0, v219
	v_add_f32_e32 v219, v177, v219
	v_cvt_pk_fp8_f32 v247, v0, v177
	v_add_f32_e32 v219, v179, v219
	v_add_f32_e32 v219, v254, v219
	v_cvt_pk_fp8_f32 v247, v179, v254 op_sel:[0,0,1]
	ds_read_b128 v[82:85], v213 offset:51200
	ds_read_b128 v[86:89], v214 offset:51200
	s_waitcnt lgkmcnt(2)
	v_mfma_scale_f32_32x32x64_f8f6f4 v[98:113], v[222:229], v[146:153], v[230:245], v194, v193 op_sel_hi:[0,0,0]
	ds_read_b128 v[222:225], v213 offset:55296
	ds_read_b128 v[226:229], v214 offset:55296
	v_exp_f32_e32 v0, v90
	v_exp_f32_e32 v177, v91
	v_exp_f32_e32 v179, v92
	v_exp_f32_e32 v254, v93
	v_add_f32_e32 v219, v0, v219
	v_add_f32_e32 v219, v177, v219
	v_cvt_pk_fp8_f32 v248, v0, v177
	v_add_f32_e32 v219, v179, v219
	v_add_f32_e32 v219, v254, v219
	v_cvt_pk_fp8_f32 v248, v179, v254 op_sel:[0,0,1]
	v_exp_f32_e32 v0, v94
	v_exp_f32_e32 v177, v95
	v_exp_f32_e32 v179, v96
	v_exp_f32_e32 v254, v97
	v_add_f32_e32 v219, v0, v219
	v_add_f32_e32 v219, v177, v219
	v_cvt_pk_fp8_f32 v249, v0, v177
	v_add_f32_e32 v219, v179, v219
	v_add_f32_e32 v219, v254, v219
	v_cvt_pk_fp8_f32 v249, v179, v254 op_sel:[0,0,1]
	ds_read_b128 v[90:93], v185 offset:59392
	ds_read_b128 v[94:97], v186 offset:59392
	s_waitcnt lgkmcnt(4)
	v_mfma_scale_f32_32x32x64_f8f6f4 v[114:129], v[82:89], v[138:145], v[114:129], v194, v193 op_sel_hi:[0,0,0]
	v_exp_f32_e32 v0, v66
	v_exp_f32_e32 v177, v67
	v_exp_f32_e32 v179, v68
	v_exp_f32_e32 v254, v69
	v_add_f32_e32 v219, v0, v219
	v_add_f32_e32 v219, v177, v219
	v_cvt_pk_fp8_f32 v250, v0, v177
	v_add_f32_e32 v219, v179, v219
	v_add_f32_e32 v219, v254, v219
	v_cvt_pk_fp8_f32 v250, v179, v254 op_sel:[0,0,1]
	s_waitcnt lgkmcnt(2)
	v_mfma_scale_f32_32x32x64_f8f6f4 v[98:113], v[222:229], v[138:145], v[98:113], v194, v193 op_sel_hi:[0,0,0]
	ds_read_b128 v[222:225], v185 offset:61440
	ds_read_b128 v[226:229], v186 offset:61440
	v_exp_f32_e32 v0, v70
	v_exp_f32_e32 v177, v71
	v_exp_f32_e32 v179, v72
	v_exp_f32_e32 v254, v73
	v_add_f32_e32 v219, v0, v219
	v_add_f32_e32 v219, v177, v219
	v_cvt_pk_fp8_f32 v251, v0, v177
	v_add_f32_e32 v219, v179, v219
	v_add_f32_e32 v219, v254, v219
	v_cvt_pk_fp8_f32 v251, v179, v254 op_sel:[0,0,1]
	v_exp_f32_e32 v0, v74
	v_exp_f32_e32 v177, v75
	v_exp_f32_e32 v179, v76
	v_exp_f32_e32 v254, v77
	v_add_f32_e32 v219, v0, v219
	v_add_f32_e32 v219, v177, v219
	v_cvt_pk_fp8_f32 v252, v0, v177
	v_add_f32_e32 v219, v179, v219
	v_add_f32_e32 v219, v254, v219
	v_cvt_pk_fp8_f32 v252, v179, v254 op_sel:[0,0,1]
	s_waitcnt lgkmcnt(2)
	v_mfma_scale_f32_32x32x64_f8f6f4 v[114:129], v[90:97], v[130:137], v[114:129], v194, v193 op_sel_hi:[0,0,0]
	v_exp_f32_e32 v0, v78
	v_exp_f32_e32 v177, v79
	v_exp_f32_e32 v179, v80
	v_exp_f32_e32 v254, v81
	v_add_f32_e32 v219, v0, v219
	v_add_f32_e32 v219, v177, v219
	v_cvt_pk_fp8_f32 v253, v0, v177
	v_add_f32_e32 v219, v179, v219
	v_add_f32_e32 v219, v254, v219
	v_cvt_pk_fp8_f32 v253, v179, v254 op_sel:[0,0,1]
	ds_read_b128 v[90:93], v185 offset:8192
	ds_read_b128 v[94:97], v186 offset:8192
	ds_read_b128 v[82:85], v185 offset:10240
	ds_read_b128 v[86:89], v186 offset:10240
	ds_read_b128 v[74:77], v185 offset:12288
	ds_read_b128 v[78:81], v186 offset:12288
	ds_read_b128 v[66:69], v185 offset:14336
	ds_read_b128 v[70:73], v186 offset:14336
	s_waitcnt lgkmcnt(8)
	v_mfma_scale_f32_32x32x64_f8f6f4 v[98:113], v[222:229], v[130:137], v[98:113], v194, v193 op_sel_hi:[0,0,0]
	v_mov_b32_e32 v0, v219
	s_nop 1
	v_permlane32_swap_b32_e32 v219, v0
	v_add_f32_e32 v219, v219, v0
	v_fma_f32 v209, v209, v218, v219
	v_max_f32_e32 v177, v114, v115
	v_max3_f32 v177, v177, v116, v117
	v_max3_f32 v177, v177, v118, v119
	v_max3_f32 v177, v177, v120, v121
	v_max3_f32 v177, v177, v122, v123
	v_max3_f32 v177, v177, v124, v125
	v_max3_f32 v177, v177, v126, v127
	v_max3_f32 v177, v177, v128, v129
	s_waitcnt lgkmcnt(6)
	v_mfma_scale_f32_32x32x64_f8f6f4 v[50:65], v[246:253], v[90:97], v[50:65], v194, v194 op_sel_hi:[0,0,0]
	s_waitcnt lgkmcnt(4)
	v_mfma_scale_f32_32x32x64_f8f6f4 v[34:49], v[246:253], v[82:89], v[34:49], v194, v194 op_sel_hi:[0,0,0]
	s_waitcnt vmcnt(0)
	ds_write_b128 v210, v[158:161]
	ds_write_b128 v211, v[162:165] offset:16384
	ds_write_b128 v212, v[154:157] offset:32768
	s_waitcnt lgkmcnt(5)
	v_mfma_scale_f32_32x32x64_f8f6f4 v[18:33], v[246:253], v[74:81], v[18:33], v194, v194 op_sel_hi:[0,0,0]
	s_waitcnt lgkmcnt(0)
	s_barrier
	s_waitcnt lgkmcnt(0)
	v_mfma_scale_f32_32x32x64_f8f6f4 v[2:17], v[246:253], v[66:73], v[2:17], v194, v194 op_sel_hi:[0,0,0]
	v_max_f32_e32 v0, v98, v99
	v_max3_f32 v0, v0, v100, v101
	v_max3_f32 v0, v0, v102, v103
	v_max3_f32 v0, v0, v104, v105
	v_max3_f32 v0, v0, v106, v107
	v_max3_f32 v0, v0, v108, v109
	v_max3_f32 v0, v0, v110, v111
	v_max3_f32 v0, v0, v112, v113
	v_max_f32_e32 v177, v177, v0
	v_mov_b32_e32 v0, v177
	v_mov_b32_e32 v221, 1.0
	s_nop 0
	v_permlane32_swap_b32_e32 v177, v0
	v_max_f32_e32 v177, v177, v0
	v_cmp_ge_f32_e32 vcc, s90, v177
	s_cmp_eq_u64 vcc, exec
	s_cbranch_scc0 .Lmla_h4_newmax
; __device__ __forceinline__ void finishSM9(f32x16& p0, f32x16& p1, float alpha, float& l_reg, v8i32& p8) {
; #pragma unroll
;   for (int r = 0; r < 16; ++r) { p0[r] = __builtin_amdgcn_exp2f(p0[r]); p1[r] = __builtin_amdgcn_exp2f(p1[r]); }
;   float ps = 0;
; #pragma unroll
;   for (int r = 0; r < 16; ++r) ps += p0[r];
; #pragma unroll
;   for (int r = 0; r < 16; ++r) ps += p1[r];
;   { auto rr = __builtin_amdgcn_permlane32_swap(__float_as_uint(ps), __float_as_uint(ps), false, false);
;     ps = __uint_as_float(rr[0]) + __uint_as_float(rr[1]); }
;   l_reg = l_reg * alpha + ps;
; #pragma unroll
;   for (int g = 0; g < 4; ++g) {
;     int w = __builtin_amdgcn_cvt_pk_fp8_f32(p0[4 * g], p0[4 * g + 1], 0, false); p8[g] = __builtin_amdgcn_cvt_pk_fp8_f32(p0[4 * g + 2], p0[4 * g + 3], w, true);
;     int u = __builtin_amdgcn_cvt_pk_fp8_f32(p1[4 * g], p1[4 * g + 1], 0, false); p8[4 + g] = __builtin_amdgcn_cvt_pk_fp8_f32(p1[4 * g + 2], p1[4 * g + 3], u, true); }
; }
; __device__ __forceinline__ void pv8(f32x16* o, const char* Vt, const v8i32 p8, int r32, int hi) {
;   const int sw = (r32 >> 2) & 3, a0 = r32 * 64 + (((hi * 2) ^ sw) << 4), a1 = r32 * 64 + (((hi * 2 + 1) ^ sw) << 4);
; #pragma unroll
;   for (int d0 = 0; d0 < 4; ++d0) {
;     const v8i32 vf = cat8(*reinterpret_cast<const v4i32*>(Vt + d0 * 2048 + a0), *reinterpret_cast<const v4i32*>(Vt + d0 * 2048 + a1));
;     o[d0] = __builtin_amdgcn_mfma_scale_f32_32x32x64_f8f6f4(p8, vf, o[d0], 0, 0, 0, 127, 0, 127); }
; }
; __device__ __forceinline__ void qkt9(f32x16& p0, f32x16& p1, const char* Kn, const char* Kr, const v8i32* qf, const float init, int r32, int hi) {
; #pragma unroll
;   for (int r = 0; r < 16; ++r) { p0[r] = init; p1[r] = init; }
; #pragma unroll
;   for (int s = 0; s < 2; ++s) { const int c0 = s * 4 + hi * 2;
;     const v8i32 a0 = cat8(*reinterpret_cast<const v4i32*>(Kn + KN8SW(r32, c0)), *reinterpret_cast<const v4i32*>(Kn + KN8SW(r32, c0 + 1)));
;     const v8i32 a1 = cat8(*reinterpret_cast<const v4i32*>(Kn + 4096 + KN8SW(r32, c0)), *reinterpret_cast<const v4i32*>(Kn + 4096 + KN8SW(r32, c0 + 1)));
;     p0 = __builtin_amdgcn_mfma_scale_f32_32x32x64_f8f6f4(a0, qf[s], p0, 0, 0, 0, 127, 0, 124);
;     p1 = __builtin_amdgcn_mfma_scale_f32_32x32x64_f8f6f4(a1, qf[s], p1, 0, 0, 0, 127, 0, 124); }
;   { const int c0 = hi * 2;
.Lmla_h4_cont:
	global_load_dwordx4 v[158:161], v176, s[18:19]
	global_load_dwordx4 v[162:165], v178, s[16:17]
	global_load_dwordx4 v[154:157], v[180:181], off
	ds_read_b128 v[82:85], v215 offset:16384
	ds_read_b128 v[86:89], v216 offset:16384
	ds_read_b128 v[222:225], v215 offset:20480
	ds_read_b128 v[226:229], v216 offset:20480
	v_add_u32_e32 v176, 0x2000, v176
	v_add_u32_e32 v178, 0x20000, v178
	s_mov_b64 s[20:21], 0x1000
	v_lshl_add_u64 v[180:181], v[180:181], 0, s[20:21]
	v_exp_f32_e32 v0, v114
	v_exp_f32_e32 v177, v115
	v_exp_f32_e32 v179, v116
	v_exp_f32_e32 v254, v117
	v_add_f32_e32 v219, v0, v177
	v_cvt_pk_fp8_f32 v246, v0, v177
	v_add_f32_e32 v219, v179, v219
	v_add_f32_e32 v219, v254, v219
	v_cvt_pk_fp8_f32 v246, v179, v254 op_sel:[0,0,1]
	s_waitcnt lgkmcnt(2)
	v_mfma_scale_f32_32x32x64_f8f6f4 v[82:97], v[82:89], v[146:153], v[230:245], v194, v193 op_sel_hi:[0,0,0]
	v_exp_f32_e32 v0, v118
	v_exp_f32_e32 v177, v119
	v_exp_f32_e32 v179, v120
	v_exp_f32_e32 v254, v121
	v_add_f32_e32 v219, v0, v219
	v_add_f32_e32 v219, v177, v219
	v_cvt_pk_fp8_f32 v247, v0, v177
	v_add_f32_e32 v219, v179, v219
	v_add_f32_e32 v219, v254, v219
	v_cvt_pk_fp8_f32 v247, v179, v254 op_sel:[0,0,1]
	ds_read_b128 v[114:117], v213 offset:16384
	ds_read_b128 v[118:121], v214 offset:16384
	s_waitcnt lgkmcnt(2)
	v_mfma_scale_f32_32x32x64_f8f6f4 v[66:81], v[222:229], v[146:153], v[230:245], v194, v193 op_sel_hi:[0,0,0]
	ds_read_b128 v[222:225], v213 offset:20480
	ds_read_b128 v[226:229], v214 offset:20480
	v_exp_f32_e32 v0, v122
	v_exp_f32_e32 v177, v123
	v_exp_f32_e32 v179, v124
	v_exp_f32_e32 v254, v125
	v_add_f32_e32 v219, v0, v219
	v_add_f32_e32 v219, v177, v219
	v_cvt_pk_fp8_f32 v248, v0, v177
	v_add_f32_e32 v219, v179, v219
	v_add_f32_e32 v219, v254, v219
	v_cvt_pk_fp8_f32 v248, v179, v254 op_sel:[0,0,1]
	v_exp_f32_e32 v0, v126
	v_exp_f32_e32 v177, v127
	v_exp_f32_e32 v179, v128
	v_exp_f32_e32 v254, v129
	v_add_f32_e32 v219, v0, v219
	v_add_f32_e32 v219, v177, v219
	v_cvt_pk_fp8_f32 v249, v0, v177
	v_add_f32_e32 v219, v179, v219
	v_add_f32_e32 v219, v254, v219
	v_cvt_pk_fp8_f32 v249, v179, v254 op_sel:[0,0,1]
	ds_read_b128 v[122:125], v185 offset:32768
	ds_read_b128 v[126:129], v186 offset:32768
	s_waitcnt lgkmcnt(4)
	v_mfma_scale_f32_32x32x64_f8f6f4 v[82:97], v[114:121], v[138:145], v[82:97], v194, v193 op_sel_hi:[0,0,0]
	v_exp_f32_e32 v0, v98
	v_exp_f32_e32 v177, v99
	v_exp_f32_e32 v179, v100
	v_exp_f32_e32 v254, v101
	v_add_f32_e32 v219, v0, v219
	v_add_f32_e32 v219, v177, v219
	v_cvt_pk_fp8_f32 v250, v0, v177
	v_add_f32_e32 v219, v179, v219
	v_add_f32_e32 v219, v254, v219
	v_cvt_pk_fp8_f32 v250, v179, v254 op_sel:[0,0,1]
	s_waitcnt lgkmcnt(2)
	v_mfma_scale_f32_32x32x64_f8f6f4 v[66:81], v[222:229], v[138:145], v[66:81], v194, v193 op_sel_hi:[0,0,0]
	ds_read_b128 v[222:225], v185 offset:34816
	ds_read_b128 v[226:229], v186 offset:34816
	v_exp_f32_e32 v0, v102
	v_exp_f32_e32 v177, v103
	v_exp_f32_e32 v179, v104
	v_exp_f32_e32 v254, v105
	v_add_f32_e32 v219, v0, v219
	v_add_f32_e32 v219, v177, v219
	v_cvt_pk_fp8_f32 v251, v0, v177
	v_add_f32_e32 v219, v179, v219
	v_add_f32_e32 v219, v254, v219
	v_cvt_pk_fp8_f32 v251, v179, v254 op_sel:[0,0,1]
	v_exp_f32_e32 v0, v106
	v_exp_f32_e32 v177, v107
	v_exp_f32_e32 v179, v108
	v_exp_f32_e32 v254, v109
	v_add_f32_e32 v219, v0, v219
	v_add_f32_e32 v219, v177, v219
	v_cvt_pk_fp8_f32 v252, v0, v177
	v_add_f32_e32 v219, v179, v219
	v_add_f32_e32 v219, v254, v219
	v_cvt_pk_fp8_f32 v252, v179, v254 op_sel:[0,0,1]
	s_waitcnt lgkmcnt(2)
	v_mfma_scale_f32_32x32x64_f8f6f4 v[82:97], v[122:129], v[130:137], v[82:97], v194, v193 op_sel_hi:[0,0,0]
	v_exp_f32_e32 v0, v110
	v_exp_f32_e32 v177, v111
	v_exp_f32_e32 v179, v112
	v_exp_f32_e32 v254, v113
	v_add_f32_e32 v219, v0, v219
	v_add_f32_e32 v219, v177, v219
	v_cvt_pk_fp8_f32 v253, v0, v177
	v_add_f32_e32 v219, v179, v219
	v_add_f32_e32 v219, v254, v219
	v_cvt_pk_fp8_f32 v253, v179, v254 op_sel:[0,0,1]
	ds_read_b128 v[122:125], v185 offset:43008
	ds_read_b128 v[126:129], v186 offset:43008
	ds_read_b128 v[114:117], v185 offset:45056
	ds_read_b128 v[118:121], v186 offset:45056
	ds_read_b128 v[106:109], v185 offset:47104
	ds_read_b128 v[110:113], v186 offset:47104
	ds_read_b128 v[98:101], v185 offset:49152
	ds_read_b128 v[102:105], v186 offset:49152
	s_waitcnt lgkmcnt(8)
	v_mfma_scale_f32_32x32x64_f8f6f4 v[66:81], v[222:229], v[130:137], v[66:81], v194, v193 op_sel_hi:[0,0,0]
	v_mov_b32_e32 v0, v219
	s_nop 1
	v_permlane32_swap_b32_e32 v219, v0
	v_add_f32_e32 v219, v219, v0
	v_fma_f32 v209, v209, v221, v219
	v_max_f32_e32 v177, v82, v83
	v_max3_f32 v177, v177, v84, v85
	v_max3_f32 v177, v177, v86, v87
	v_max3_f32 v177, v177, v88, v89
	v_max3_f32 v177, v177, v90, v91
	v_max3_f32 v177, v177, v92, v93
	v_max3_f32 v177, v177, v94, v95
	v_max3_f32 v177, v177, v96, v97
	s_waitcnt lgkmcnt(6)
	v_mfma_scale_f32_32x32x64_f8f6f4 v[50:65], v[246:253], v[122:129], v[50:65], v194, v194 op_sel_hi:[0,0,0]
	s_waitcnt lgkmcnt(4)
	v_mfma_scale_f32_32x32x64_f8f6f4 v[34:49], v[246:253], v[114:121], v[34:49], v194, v194 op_sel_hi:[0,0,0]
	s_waitcnt vmcnt(0)
	ds_write_b128 v210, v[158:161] offset:8192
	ds_write_b128 v211, v[162:165] offset:24576
	ds_write_b128 v212, v[154:157] offset:36864
	s_waitcnt lgkmcnt(5)
	v_mfma_scale_f32_32x32x64_f8f6f4 v[18:33], v[246:253], v[106:113], v[18:33], v194, v194 op_sel_hi:[0,0,0]
	s_waitcnt lgkmcnt(0)
	s_barrier
	s_waitcnt lgkmcnt(0)
	v_mfma_scale_f32_32x32x64_f8f6f4 v[2:17], v[246:253], v[98:105], v[2:17], v194, v194 op_sel_hi:[0,0,0]
	v_max_f32_e32 v0, v66, v67
	v_max3_f32 v0, v0, v68, v69
	v_max3_f32 v0, v0, v70, v71
	v_max3_f32 v0, v0, v72, v73
	v_max3_f32 v0, v0, v74, v75
	v_max3_f32 v0, v0, v76, v77
	v_max3_f32 v0, v0, v78, v79
	v_max3_f32 v0, v0, v80, v81
	v_max_f32_e32 v177, v177, v0
	v_mov_b32_e32 v0, v177
	v_mov_b32_e32 v218, 1.0
	s_nop 0
	v_permlane32_swap_b32_e32 v177, v0
	v_max_f32_e32 v177, v177, v0
	v_cmp_ge_f32_e32 vcc, s90, v177
	s_cmp_eq_u64 vcc, exec
	s_cbranch_scc0 .Lmla_h5_newmax
; __device__ __forceinline__ void finishSM9(f32x16& p0, f32x16& p1, float alpha, float& l_reg, v8i32& p8) {
; #pragma unroll
;   for (int r = 0; r < 16; ++r) { p0[r] = __builtin_amdgcn_exp2f(p0[r]); p1[r] = __builtin_amdgcn_exp2f(p1[r]); }
;   float ps = 0;
; #pragma unroll
;   for (int r = 0; r < 16; ++r) ps += p0[r];
; #pragma unroll
;   for (int r = 0; r < 16; ++r) ps += p1[r];
;   { auto rr = __builtin_amdgcn_permlane32_swap(__float_as_uint(ps), __float_as_uint(ps), false, false);
;     ps = __uint_as_float(rr[0]) + __uint_as_float(rr[1]); }
;   l_reg = l_reg * alpha + ps;
; #pragma unroll
;   for (int g = 0; g < 4; ++g) {
;     int w = __builtin_amdgcn_cvt_pk_fp8_f32(p0[4 * g], p0[4 * g + 1], 0, false); p8[g] = __builtin_amdgcn_cvt_pk_fp8_f32(p0[4 * g + 2], p0[4 * g + 3], w, true);
;     int u = __builtin_amdgcn_cvt_pk_fp8_f32(p1[4 * g], p1[4 * g + 1], 0, false); p8[4 + g] = __builtin_amdgcn_cvt_pk_fp8_f32(p1[4 * g + 2], p1[4 * g + 3], u, true); }
; }
; __device__ __forceinline__ void pv8(f32x16* o, const char* Vt, const v8i32 p8, int r32, int hi) {
;   const int sw = (r32 >> 2) & 3, a0 = r32 * 64 + (((hi * 2) ^ sw) << 4), a1 = r32 * 64 + (((hi * 2 + 1) ^ sw) << 4);
; #pragma unroll
;   for (int d0 = 0; d0 < 4; ++d0) {
;     const v8i32 vf = cat8(*reinterpret_cast<const v4i32*>(Vt + d0 * 2048 + a0), *reinterpret_cast<const v4i32*>(Vt + d0 * 2048 + a1));
;     o[d0] = __builtin_amdgcn_mfma_scale_f32_32x32x64_f8f6f4(p8, vf, o[d0], 0, 0, 0, 127, 0, 127); }
; }
; __device__ __forceinline__ void qkt9(f32x16& p0, f32x16& p1, const char* Kn, const char* Kr, const v8i32* qf, const float init, int r32, int hi) {
; #pragma unroll
;   for (int r = 0; r < 16; ++r) { p0[r] = init; p1[r] = init; }
; #pragma unroll
;   for (int s = 0; s < 2; ++s) { const int c0 = s * 4 + hi * 2;
;     const v8i32 a0 = cat8(*reinterpret_cast<const v4i32*>(Kn + KN8SW(r32, c0)), *reinterpret_cast<const v4i32*>(Kn + KN8SW(r32, c0 + 1)));
;     const v8i32 a1 = cat8(*reinterpret_cast<const v4i32*>(Kn + 4096 + KN8SW(r32, c0)), *reinterpret_cast<const v4i32*>(Kn + 4096 + KN8SW(r32, c0 + 1)));
;     p0 = __builtin_amdgcn_mfma_scale_f32_32x32x64_f8f6f4(a0, qf[s], p0, 0, 0, 0, 127, 0, 124);
;     p1 = __builtin_amdgcn_mfma_scale_f32_32x32x64_f8f6f4(a1, qf[s], p1, 0, 0, 0, 127, 0, 124); }
;   { const int c0 = hi * 2;
.Lmla_h5_cont:
	s_add_i32 s30, s30, 1
	s_cmpk_lt_u32 s30, 42
	s_cbranch_scc1 .LBB0_1321
	global_load_dwordx4 v[158:161], v176, s[18:19]
	global_load_dwordx4 v[162:165], v178, s[16:17]
	global_load_dwordx4 v[154:157], v[180:181], off
	ds_read_b128 v[114:117], v215 offset:24576
	ds_read_b128 v[118:121], v216 offset:24576
	ds_read_b128 v[222:225], v215 offset:28672
	ds_read_b128 v[226:229], v216 offset:28672
	v_add_u32_e32 v176, 0x2000, v176
	v_add_u32_e32 v178, 0x20000, v178
	s_mov_b64 s[20:21], 0x1000
	v_lshl_add_u64 v[180:181], v[180:181], 0, s[20:21]
	v_exp_f32_e32 v0, v82
	v_exp_f32_e32 v177, v83
	v_exp_f32_e32 v179, v84
	v_exp_f32_e32 v254, v85
	v_add_f32_e32 v219, v0, v177
	v_cvt_pk_fp8_f32 v246, v0, v177
	v_add_f32_e32 v219, v179, v219
	v_add_f32_e32 v219, v254, v219
	v_cvt_pk_fp8_f32 v246, v179, v254 op_sel:[0,0,1]
	s_waitcnt lgkmcnt(2)
	v_mfma_scale_f32_32x32x64_f8f6f4 v[114:129], v[114:121], v[146:153], v[230:245], v194, v193 op_sel_hi:[0,0,0]
	v_exp_f32_e32 v0, v86
	v_exp_f32_e32 v177, v87
	v_exp_f32_e32 v179, v88
	v_exp_f32_e32 v254, v89
	v_add_f32_e32 v219, v0, v219
	v_add_f32_e32 v219, v177, v219
	v_cvt_pk_fp8_f32 v247, v0, v177
	v_add_f32_e32 v219, v179, v219
	v_add_f32_e32 v219, v254, v219
	v_cvt_pk_fp8_f32 v247, v179, v254 op_sel:[0,0,1]
	ds_read_b128 v[82:85], v213 offset:24576
	ds_read_b128 v[86:89], v214 offset:24576
	s_waitcnt lgkmcnt(2)
	v_mfma_scale_f32_32x32x64_f8f6f4 v[98:113], v[222:229], v[146:153], v[230:245], v194, v193 op_sel_hi:[0,0,0]
	ds_read_b128 v[222:225], v213 offset:28672
	ds_read_b128 v[226:229], v214 offset:28672
	v_exp_f32_e32 v0, v90
	v_exp_f32_e32 v177, v91
	v_exp_f32_e32 v179, v92
	v_exp_f32_e32 v254, v93
	v_add_f32_e32 v219, v0, v219
	v_add_f32_e32 v219, v177, v219
	v_cvt_pk_fp8_f32 v248, v0, v177
	v_add_f32_e32 v219, v179, v219
	v_add_f32_e32 v219, v254, v219
	v_cvt_pk_fp8_f32 v248, v179, v254 op_sel:[0,0,1]
	v_exp_f32_e32 v0, v94
	v_exp_f32_e32 v177, v95
	v_exp_f32_e32 v179, v96
	v_exp_f32_e32 v254, v97
	v_add_f32_e32 v219, v0, v219
	v_add_f32_e32 v219, v177, v219
	v_cvt_pk_fp8_f32 v249, v0, v177
	v_add_f32_e32 v219, v179, v219
	v_add_f32_e32 v219, v254, v219
	v_cvt_pk_fp8_f32 v249, v179, v254 op_sel:[0,0,1]
	ds_read_b128 v[90:93], v185 offset:36864
	ds_read_b128 v[94:97], v186 offset:36864
	s_waitcnt lgkmcnt(4)
	v_mfma_scale_f32_32x32x64_f8f6f4 v[114:129], v[82:89], v[138:145], v[114:129], v194, v193 op_sel_hi:[0,0,0]
	v_exp_f32_e32 v0, v66
	v_exp_f32_e32 v177, v67
	v_exp_f32_e32 v179, v68
	v_exp_f32_e32 v254, v69
	v_add_f32_e32 v219, v0, v219
	v_add_f32_e32 v219, v177, v219
	v_cvt_pk_fp8_f32 v250, v0, v177
	v_add_f32_e32 v219, v179, v219
	v_add_f32_e32 v219, v254, v219
	v_cvt_pk_fp8_f32 v250, v179, v254 op_sel:[0,0,1]
	s_waitcnt lgkmcnt(2)
	v_mfma_scale_f32_32x32x64_f8f6f4 v[98:113], v[222:229], v[138:145], v[98:113], v194, v193 op_sel_hi:[0,0,0]
	ds_read_b128 v[222:225], v185 offset:38912
	ds_read_b128 v[226:229], v186 offset:38912
	v_exp_f32_e32 v0, v70
	v_exp_f32_e32 v177, v71
	v_exp_f32_e32 v179, v72
	v_exp_f32_e32 v254, v73
	v_add_f32_e32 v219, v0, v219
	v_add_f32_e32 v219, v177, v219
	v_cvt_pk_fp8_f32 v251, v0, v177
	v_add_f32_e32 v219, v179, v219
	v_add_f32_e32 v219, v254, v219
	v_cvt_pk_fp8_f32 v251, v179, v254 op_sel:[0,0,1]
	v_exp_f32_e32 v0, v74
	v_exp_f32_e32 v177, v75
	v_exp_f32_e32 v179, v76
	v_exp_f32_e32 v254, v77
	v_add_f32_e32 v219, v0, v219
	v_add_f32_e32 v219, v177, v219
	v_cvt_pk_fp8_f32 v252, v0, v177
	v_add_f32_e32 v219, v179, v219
	v_add_f32_e32 v219, v254, v219
	v_cvt_pk_fp8_f32 v252, v179, v254 op_sel:[0,0,1]
	s_waitcnt lgkmcnt(2)
	v_mfma_scale_f32_32x32x64_f8f6f4 v[114:129], v[90:97], v[130:137], v[114:129], v194, v193 op_sel_hi:[0,0,0]
	v_exp_f32_e32 v0, v78
	v_exp_f32_e32 v177, v79
	v_exp_f32_e32 v179, v80
	v_exp_f32_e32 v254, v81
	v_add_f32_e32 v219, v0, v219
	v_add_f32_e32 v219, v177, v219
	v_cvt_pk_fp8_f32 v253, v0, v177
	v_add_f32_e32 v219, v179, v219
	v_add_f32_e32 v219, v254, v219
	v_cvt_pk_fp8_f32 v253, v179, v254 op_sel:[0,0,1]
	ds_read_b128 v[90:93], v185 offset:0
	ds_read_b128 v[94:97], v186 offset:0
	ds_read_b128 v[82:85], v185 offset:2048
	ds_read_b128 v[86:89], v186 offset:2048
	ds_read_b128 v[74:77], v185 offset:4096
	ds_read_b128 v[78:81], v186 offset:4096
	ds_read_b128 v[66:69], v185 offset:6144
	ds_read_b128 v[70:73], v186 offset:6144
	s_waitcnt lgkmcnt(8)
	v_mfma_scale_f32_32x32x64_f8f6f4 v[98:113], v[222:229], v[130:137], v[98:113], v194, v193 op_sel_hi:[0,0,0]
	v_mov_b32_e32 v0, v219
	s_nop 1
	v_permlane32_swap_b32_e32 v219, v0
	v_add_f32_e32 v219, v219, v0
	v_fma_f32 v209, v209, v218, v219
	v_max_f32_e32 v177, v114, v115
	v_max3_f32 v177, v177, v116, v117
	v_max3_f32 v177, v177, v118, v119
	v_max3_f32 v177, v177, v120, v121
	v_max3_f32 v177, v177, v122, v123
	v_max3_f32 v177, v177, v124, v125
	v_max3_f32 v177, v177, v126, v127
	v_max3_f32 v177, v177, v128, v129
	s_waitcnt lgkmcnt(6)
	v_mfma_scale_f32_32x32x64_f8f6f4 v[50:65], v[246:253], v[90:97], v[50:65], v194, v194 op_sel_hi:[0,0,0]
	s_waitcnt lgkmcnt(4)
	v_mfma_scale_f32_32x32x64_f8f6f4 v[34:49], v[246:253], v[82:89], v[34:49], v194, v194 op_sel_hi:[0,0,0]
	s_waitcnt vmcnt(0)
	ds_write_b128 v210, v[158:161] offset:43008
	ds_write_b128 v211, v[162:165] offset:51200
	ds_write_b128 v212, v[154:157] offset:59392
	s_waitcnt lgkmcnt(5)
	v_mfma_scale_f32_32x32x64_f8f6f4 v[18:33], v[246:253], v[74:81], v[18:33], v194, v194 op_sel_hi:[0,0,0]
	s_waitcnt lgkmcnt(0)
	s_barrier
	s_waitcnt lgkmcnt(0)
	v_mfma_scale_f32_32x32x64_f8f6f4 v[2:17], v[246:253], v[66:73], v[2:17], v194, v194 op_sel_hi:[0,0,0]
	v_max_f32_e32 v0, v98, v99
	v_max3_f32 v0, v0, v100, v101
	v_max3_f32 v0, v0, v102, v103
	v_max3_f32 v0, v0, v104, v105
	v_max3_f32 v0, v0, v106, v107
	v_max3_f32 v0, v0, v108, v109
	v_max3_f32 v0, v0, v110, v111
	v_max3_f32 v0, v0, v112, v113
	v_max_f32_e32 v177, v177, v0
	v_mov_b32_e32 v0, v177
	v_mov_b32_e32 v221, 1.0
	s_nop 0
	v_permlane32_swap_b32_e32 v177, v0
	v_max_f32_e32 v177, v177, v0
	v_cmp_ge_f32_e32 vcc, s90, v177
	s_cmp_eq_u64 vcc, exec
	s_cbranch_scc0 .Lmla_p0_newmax
